# as v59 but the slices sit right before each staging-loop barrier instead of right after it
# baseline (speedup 1.0000x reference)
; __device__ __forceinline__ void rwkv_scan_phase(Frame& F, const bf16* RKV, const float* WAG, const bf16* AGB, const float* k_k, const float* k_a, const float* r_k, bf16* Y, float* BS, float* ST2) {
;     ...
;             constexpr int NCH = SEQ / SC_T;
;             v2u RAh[2][4], RBh[2][4]; f32x4 RAw[2], RBw[2];
;             ST_LOAD(RA, 0); ST_LOAD(RB, 1);
;             ST_PROC(RA, 0);
;             __syncthreads();
;             for (int ci = 0; ci < NCH; ci += 2) {
;                 if (ci >= 1) ST_FLUSH(ci - 1);
;                 if (ci + 2 < NCH) ST_LOAD(RA, ci + 2);
;                 ST_PROC(RB, ci + 1);
;                 __syncthreads();
.LBB0_1797:
	s_or_b64 exec, exec, s[60:61]
	v_add_f32_e32 v181, v181, v182
	v_rsq_f32_e32 v181, v181
	ds_write_b128 v172, v[28:31] offset:45056
	ds_write_b128 v172, v[24:27] offset:53248
	ds_write_b128 v172, v[32:35] offset:61440
	v_max_f32_e64 v28, -v181, s35
	v_pk_mul_f32 v[30:31], v[142:143], v[28:29] op_sel_hi:[1,0]
	v_pk_mul_f32 v[28:29], v[144:145], v[28:29] op_sel_hi:[1,0]
	ds_write_b128 v178, v[28:31]
	v_pk_mul_f32 v[30:31], v[30:31], v[140:141] neg_lo:[1,0] neg_hi:[1,0]
	v_pk_mul_f32 v[28:29], v[28:29], v[138:139] neg_lo:[1,0] neg_hi:[1,0]
	ds_write_b128 v179, v[28:31]
	s_and_saveexec_b64 s[60:61], s[8:9]
	v_lshlrev_b32_e32 v28, 16, v64
	v_and_b32_e32 v29, 0xffff0000, v64
	v_lshlrev_b32_e32 v30, 16, v65
	v_and_b32_e32 v31, 0xffff0000, v65
	ds_write_b128 v180, v[28:31]
	s_or_b64 exec, exec, s[60:61]
	s_cmp_lt_u32 s80, 4
	s_cbranch_scc1 .Lcsap_adv
	s_cmp_eq_u32 s69, 0
	s_cbranch_scc1 .Lcsap_adv
	v_mbcnt_lo_u32_b32 v243, -1, 0
	v_mbcnt_hi_u32_b32 v243, -1, v243
	s_sub_u32 s92, s80, 5
	s_mul_i32 s92, s92, 0x2100
	s_add_u32 s92, s92, 0x19200
	s_cmp_eq_u32 s80, 4
	s_cselect_b32 s92, 0x20800, s92
	v_lshrrev_b32_e32 v241, 3, v243
	v_and_b32_e32 v242, 7, v243
	v_mul_u32_u24_e32 v243, 132, v241
	v_lshl_add_u32 v243, v242, 4, v243
	v_add_u32_e32 v238, s92, v243
	v_mul_u32_u24_e32 v243, 0x420, v242
	v_lshl_add_u32 v243, v241, 2, v243
	v_add_u32_e32 v239, s92, v243
	v_mul_lo_u32 v243, v241, s81
	v_lshl_add_u32 v240, v242, 4, v243
	s_cmp_eq_u32 s32, 1
	s_cbranch_scc0 .Lcsap_w0
	s_waitcnt vmcnt(10)
	s_branch .Lcsap_wd
